# th1 plus 64-byte alignment of the three GEMM K-loop heads
# baseline (speedup 1.0000x reference)
.LBB0_255:
	s_ashr_i32 s17, s16, 31
	s_lshl_b64 s[8:9], s[16:17], 20
	v_readlane_b32 s18, v254, 39
	v_readlane_b32 s19, v254, 40
	s_add_u32 s18, s18, s8
	s_addc_u32 s19, s19, s9
	s_and_b64 s[8:9], s[36:37], exec
	s_cselect_b32 s8, s19, s3
	s_cselect_b32 s9, s18, s2
	s_ashr_i32 s15, s14, 31
	s_lshl_b64 s[20:21], s[14:15], 20
	s_add_u32 s20, s29, s20
	s_addc_u32 s21, s38, s21
	s_and_b64 s[26:27], s[36:37], exec
	s_cselect_b32 s15, s21, s23
	s_cselect_b32 s17, s20, s22
	s_add_u32 s2, s2, 0x80800
	s_addc_u32 s3, s3, 0
	s_add_u32 s33, s22, 0x100
	v_mov_b32_e32 v20, 0
	s_addc_u32 s34, s23, 0
	s_mov_b32 s35, -2
	v_mov_b32_e32 v21, v20
	v_mov_b32_e32 v22, v20
	v_mov_b32_e32 v23, v20
	v_mov_b32_e32 v28, v20
	v_mov_b32_e32 v29, v20
	v_mov_b32_e32 v30, v20
	v_mov_b32_e32 v31, v20
	v_mov_b32_e32 v36, v20
	v_mov_b32_e32 v37, v20
	v_mov_b32_e32 v38, v20
	v_mov_b32_e32 v39, v20
	v_mov_b32_e32 v44, v20
	v_mov_b32_e32 v45, v20
	v_mov_b32_e32 v46, v20
	v_mov_b32_e32 v47, v20
	v_mov_b32_e32 v52, v20
	v_mov_b32_e32 v53, v20
	v_mov_b32_e32 v54, v20
	v_mov_b32_e32 v55, v20
	v_mov_b32_e32 v60, v20
	v_mov_b32_e32 v61, v20
	v_mov_b32_e32 v62, v20
	v_mov_b32_e32 v63, v20
	v_mov_b32_e32 v68, v20
	v_mov_b32_e32 v69, v20
	v_mov_b32_e32 v70, v20
	v_mov_b32_e32 v71, v20
	v_mov_b32_e32 v76, v20
	v_mov_b32_e32 v77, v20
	v_mov_b32_e32 v78, v20
	v_mov_b32_e32 v79, v20
	v_mov_b32_e32 v24, v20
	v_mov_b32_e32 v25, v20
	v_mov_b32_e32 v26, v20
	v_mov_b32_e32 v27, v20
	v_mov_b32_e32 v32, v20
	v_mov_b32_e32 v33, v20
	v_mov_b32_e32 v34, v20
	v_mov_b32_e32 v35, v20
	v_mov_b32_e32 v40, v20
	v_mov_b32_e32 v41, v20
	v_mov_b32_e32 v42, v20
	v_mov_b32_e32 v43, v20
	v_mov_b32_e32 v48, v20
	v_mov_b32_e32 v49, v20
	v_mov_b32_e32 v50, v20
	v_mov_b32_e32 v51, v20
	v_mov_b32_e32 v56, v20
	v_mov_b32_e32 v57, v20
	v_mov_b32_e32 v58, v20
	v_mov_b32_e32 v59, v20
	v_mov_b32_e32 v64, v20
	v_mov_b32_e32 v65, v20
	v_mov_b32_e32 v66, v20
	v_mov_b32_e32 v67, v20
	v_mov_b32_e32 v72, v20
	v_mov_b32_e32 v73, v20
	v_mov_b32_e32 v74, v20
	v_mov_b32_e32 v75, v20
	v_mov_b32_e32 v80, v20
	v_mov_b32_e32 v81, v20
	v_mov_b32_e32 v82, v20
	v_mov_b32_e32 v83, v20
	v_mov_b32_e32 v84, v20
	v_mov_b32_e32 v85, v20
	v_mov_b32_e32 v86, v20
	v_mov_b32_e32 v87, v20
	v_mov_b32_e32 v92, v20
	v_mov_b32_e32 v93, v20
	v_mov_b32_e32 v94, v20
	v_mov_b32_e32 v95, v20
	v_mov_b32_e32 v100, v20
	v_mov_b32_e32 v101, v20
	v_mov_b32_e32 v102, v20
	v_mov_b32_e32 v103, v20
	v_mov_b32_e32 v108, v20
	v_mov_b32_e32 v109, v20
	v_mov_b32_e32 v110, v20
	v_mov_b32_e32 v111, v20
	v_mov_b32_e32 v116, v20
	v_mov_b32_e32 v117, v20
	v_mov_b32_e32 v118, v20
	v_mov_b32_e32 v119, v20
	v_mov_b32_e32 v124, v20
	v_mov_b32_e32 v125, v20
	v_mov_b32_e32 v126, v20
	v_mov_b32_e32 v127, v20
	v_mov_b32_e32 v132, v20
	v_mov_b32_e32 v133, v20
	v_mov_b32_e32 v134, v20
	v_mov_b32_e32 v135, v20
	v_mov_b32_e32 v140, v20
	v_mov_b32_e32 v141, v20
	v_mov_b32_e32 v142, v20
	v_mov_b32_e32 v143, v20
	v_mov_b32_e32 v88, v20
	v_mov_b32_e32 v89, v20
	v_mov_b32_e32 v90, v20
	v_mov_b32_e32 v91, v20
	v_mov_b32_e32 v96, v20
	v_mov_b32_e32 v97, v20
	v_mov_b32_e32 v98, v20
	v_mov_b32_e32 v99, v20
	v_mov_b32_e32 v104, v20
	v_mov_b32_e32 v105, v20
	v_mov_b32_e32 v106, v20
	v_mov_b32_e32 v107, v20
	v_mov_b32_e32 v112, v20
	v_mov_b32_e32 v113, v20
	v_mov_b32_e32 v114, v20
	v_mov_b32_e32 v115, v20
	v_mov_b32_e32 v120, v20
	v_mov_b32_e32 v121, v20
	v_mov_b32_e32 v122, v20
	v_mov_b32_e32 v123, v20
	v_mov_b32_e32 v128, v20
	v_mov_b32_e32 v129, v20
	v_mov_b32_e32 v130, v20
	v_mov_b32_e32 v131, v20
	v_mov_b32_e32 v136, v20
	v_mov_b32_e32 v137, v20
	v_mov_b32_e32 v138, v20
	v_mov_b32_e32 v139, v20
	v_mov_b32_e32 v144, v20
	v_mov_b32_e32 v145, v20
	v_mov_b32_e32 v146, v20
	v_mov_b32_e32 v147, v20
	.p2align	6

.LBB0_488:
	s_ashr_i32 s17, s16, 31
	s_lshl_b64 s[8:9], s[16:17], 20
	v_readlane_b32 s18, v254, 39
	v_readlane_b32 s19, v254, 40
	s_add_u32 s18, s18, s8
	s_addc_u32 s19, s19, s9
	s_and_b64 s[8:9], s[36:37], exec
	s_cselect_b32 s3, s19, s23
	s_cselect_b32 s6, s18, s22
	s_ashr_i32 s15, s14, 31
	s_lshl_b64 s[8:9], s[14:15], 20
	s_add_u32 s20, s28, s8
	s_addc_u32 s21, s29, s9
	s_and_b64 s[8:9], s[36:37], exec
	s_cselect_b32 s8, s21, s27
	s_cselect_b32 s9, s20, s26
	s_add_u32 s22, s22, 0x80800
	s_addc_u32 s23, s23, 0
	s_add_u32 s15, s26, 0x100
	v_mov_b32_e32 v12, 0
	s_addc_u32 s17, s27, 0
	s_mov_b32 s33, -2
	v_mov_b32_e32 v13, v12
	v_mov_b32_e32 v14, v12
	v_mov_b32_e32 v15, v12
	v_mov_b32_e32 v16, v12
	v_mov_b32_e32 v17, v12
	v_mov_b32_e32 v18, v12
	v_mov_b32_e32 v19, v12
	v_mov_b32_e32 v20, v12
	v_mov_b32_e32 v21, v12
	v_mov_b32_e32 v22, v12
	v_mov_b32_e32 v23, v12
	v_mov_b32_e32 v28, v12
	v_mov_b32_e32 v29, v12
	v_mov_b32_e32 v30, v12
	v_mov_b32_e32 v31, v12
	v_mov_b32_e32 v36, v12
	v_mov_b32_e32 v37, v12
	v_mov_b32_e32 v38, v12
	v_mov_b32_e32 v39, v12
	v_mov_b32_e32 v44, v12
	v_mov_b32_e32 v45, v12
	v_mov_b32_e32 v46, v12
	v_mov_b32_e32 v47, v12
	v_mov_b32_e32 v52, v12
	v_mov_b32_e32 v53, v12
	v_mov_b32_e32 v54, v12
	v_mov_b32_e32 v55, v12
	v_mov_b32_e32 v60, v12
	v_mov_b32_e32 v61, v12
	v_mov_b32_e32 v62, v12
	v_mov_b32_e32 v63, v12
	v_mov_b32_e32 v24, v12
	v_mov_b32_e32 v25, v12
	v_mov_b32_e32 v26, v12
	v_mov_b32_e32 v27, v12
	v_mov_b32_e32 v32, v12
	v_mov_b32_e32 v33, v12
	v_mov_b32_e32 v34, v12
	v_mov_b32_e32 v35, v12
	v_mov_b32_e32 v40, v12
	v_mov_b32_e32 v41, v12
	v_mov_b32_e32 v42, v12
	v_mov_b32_e32 v43, v12
	v_mov_b32_e32 v48, v12
	v_mov_b32_e32 v49, v12
	v_mov_b32_e32 v50, v12
	v_mov_b32_e32 v51, v12
	v_mov_b32_e32 v56, v12
	v_mov_b32_e32 v57, v12
	v_mov_b32_e32 v58, v12
	v_mov_b32_e32 v59, v12
	v_mov_b32_e32 v64, v12
	v_mov_b32_e32 v65, v12
	v_mov_b32_e32 v66, v12
	v_mov_b32_e32 v67, v12
	v_mov_b32_e32 v68, v12
	v_mov_b32_e32 v69, v12
	v_mov_b32_e32 v70, v12
	v_mov_b32_e32 v71, v12
	v_mov_b32_e32 v72, v12
	v_mov_b32_e32 v73, v12
	v_mov_b32_e32 v74, v12
	v_mov_b32_e32 v75, v12
	v_mov_b32_e32 v76, v12
	v_mov_b32_e32 v77, v12
	v_mov_b32_e32 v78, v12
	v_mov_b32_e32 v79, v12
	v_mov_b32_e32 v80, v12
	v_mov_b32_e32 v81, v12
	v_mov_b32_e32 v82, v12
	v_mov_b32_e32 v83, v12
	v_mov_b32_e32 v84, v12
	v_mov_b32_e32 v85, v12
	v_mov_b32_e32 v86, v12
	v_mov_b32_e32 v87, v12
	v_mov_b32_e32 v92, v12
	v_mov_b32_e32 v93, v12
	v_mov_b32_e32 v94, v12
	v_mov_b32_e32 v95, v12
	v_mov_b32_e32 v100, v12
	v_mov_b32_e32 v101, v12
	v_mov_b32_e32 v102, v12
	v_mov_b32_e32 v103, v12
	v_mov_b32_e32 v108, v12
	v_mov_b32_e32 v109, v12
	v_mov_b32_e32 v110, v12
	v_mov_b32_e32 v111, v12
	v_mov_b32_e32 v116, v12
	v_mov_b32_e32 v117, v12
	v_mov_b32_e32 v118, v12
	v_mov_b32_e32 v119, v12
	v_mov_b32_e32 v124, v12
	v_mov_b32_e32 v125, v12
	v_mov_b32_e32 v126, v12
	v_mov_b32_e32 v127, v12
	v_mov_b32_e32 v88, v12
	v_mov_b32_e32 v89, v12
	v_mov_b32_e32 v90, v12
	v_mov_b32_e32 v91, v12
	v_mov_b32_e32 v96, v12
	v_mov_b32_e32 v97, v12
	v_mov_b32_e32 v98, v12
	v_mov_b32_e32 v99, v12
	v_mov_b32_e32 v104, v12
	v_mov_b32_e32 v105, v12
	v_mov_b32_e32 v106, v12
	v_mov_b32_e32 v107, v12
	v_mov_b32_e32 v112, v12
	v_mov_b32_e32 v113, v12
	v_mov_b32_e32 v114, v12
	v_mov_b32_e32 v115, v12
	v_mov_b32_e32 v120, v12
	v_mov_b32_e32 v121, v12
	v_mov_b32_e32 v122, v12
	v_mov_b32_e32 v123, v12
	v_mov_b32_e32 v128, v12
	v_mov_b32_e32 v129, v12
	v_mov_b32_e32 v130, v12
	v_mov_b32_e32 v131, v12
	v_mov_b32_e32 v132, v12
	v_mov_b32_e32 v133, v12
	v_mov_b32_e32 v134, v12
	v_mov_b32_e32 v135, v12
	v_mov_b32_e32 v136, v12
	v_mov_b32_e32 v137, v12
	v_mov_b32_e32 v138, v12
	v_mov_b32_e32 v139, v12
	.p2align	6

.LBB0_831:
	s_lshl_b32 s98, s100, 1
	s_add_u32 s2, s2, s100
	s_addc_u32 s3, s3, 0
	s_add_u32 s7, s22, 0x100
	v_mov_b32_e32 v4, 0
	s_addc_u32 s8, s23, 0
	s_mov_b32 s9, 0
	v_mov_b32_e32 v5, v4
	v_mov_b32_e32 v6, v4
	v_mov_b32_e32 v7, v4
	v_mov_b32_e32 v8, v4
	v_mov_b32_e32 v9, v4
	v_mov_b32_e32 v10, v4
	v_mov_b32_e32 v11, v4
	v_mov_b32_e32 v20, v4
	v_mov_b32_e32 v21, v4
	v_mov_b32_e32 v22, v4
	v_mov_b32_e32 v23, v4
	v_mov_b32_e32 v24, v4
	v_mov_b32_e32 v25, v4
	v_mov_b32_e32 v26, v4
	v_mov_b32_e32 v27, v4
	v_mov_b32_e32 v36, v4
	v_mov_b32_e32 v37, v4
	v_mov_b32_e32 v38, v4
	v_mov_b32_e32 v39, v4
	v_mov_b32_e32 v40, v4
	v_mov_b32_e32 v41, v4
	v_mov_b32_e32 v42, v4
	v_mov_b32_e32 v43, v4
	v_mov_b32_e32 v52, v4
	v_mov_b32_e32 v53, v4
	v_mov_b32_e32 v54, v4
	v_mov_b32_e32 v55, v4
	v_mov_b32_e32 v56, v4
	v_mov_b32_e32 v57, v4
	v_mov_b32_e32 v58, v4
	v_mov_b32_e32 v59, v4
	v_mov_b32_e32 v12, v4
	v_mov_b32_e32 v13, v4
	v_mov_b32_e32 v14, v4
	v_mov_b32_e32 v15, v4
	v_mov_b32_e32 v16, v4
	v_mov_b32_e32 v17, v4
	v_mov_b32_e32 v18, v4
	v_mov_b32_e32 v19, v4
	v_mov_b32_e32 v28, v4
	v_mov_b32_e32 v29, v4
	v_mov_b32_e32 v30, v4
	v_mov_b32_e32 v31, v4
	v_mov_b32_e32 v32, v4
	v_mov_b32_e32 v33, v4
	v_mov_b32_e32 v34, v4
	v_mov_b32_e32 v35, v4
	v_mov_b32_e32 v44, v4
	v_mov_b32_e32 v45, v4
	v_mov_b32_e32 v46, v4
	v_mov_b32_e32 v47, v4
	v_mov_b32_e32 v48, v4
	v_mov_b32_e32 v49, v4
	v_mov_b32_e32 v50, v4
	v_mov_b32_e32 v51, v4
	v_mov_b32_e32 v60, v4
	v_mov_b32_e32 v61, v4
	v_mov_b32_e32 v62, v4
	v_mov_b32_e32 v63, v4
	v_mov_b32_e32 v64, v4
	v_mov_b32_e32 v65, v4
	v_mov_b32_e32 v66, v4
	v_mov_b32_e32 v67, v4
	v_mov_b32_e32 v68, v4
	v_mov_b32_e32 v69, v4
	v_mov_b32_e32 v70, v4
	v_mov_b32_e32 v71, v4
	v_mov_b32_e32 v72, v4
	v_mov_b32_e32 v73, v4
	v_mov_b32_e32 v74, v4
	v_mov_b32_e32 v75, v4
	v_mov_b32_e32 v84, v4
	v_mov_b32_e32 v85, v4
	v_mov_b32_e32 v86, v4
	v_mov_b32_e32 v87, v4
	v_mov_b32_e32 v88, v4
	v_mov_b32_e32 v89, v4
	v_mov_b32_e32 v90, v4
	v_mov_b32_e32 v91, v4
	v_mov_b32_e32 v100, v4
	v_mov_b32_e32 v101, v4
	v_mov_b32_e32 v102, v4
	v_mov_b32_e32 v103, v4
	v_mov_b32_e32 v104, v4
	v_mov_b32_e32 v105, v4
	v_mov_b32_e32 v106, v4
	v_mov_b32_e32 v107, v4
	v_mov_b32_e32 v116, v4
	v_mov_b32_e32 v117, v4
	v_mov_b32_e32 v118, v4
	v_mov_b32_e32 v119, v4
	v_mov_b32_e32 v120, v4
	v_mov_b32_e32 v121, v4
	v_mov_b32_e32 v122, v4
	v_mov_b32_e32 v123, v4
	v_mov_b32_e32 v76, v4
	v_mov_b32_e32 v77, v4
	v_mov_b32_e32 v78, v4
	v_mov_b32_e32 v79, v4
	v_mov_b32_e32 v80, v4
	v_mov_b32_e32 v81, v4
	v_mov_b32_e32 v82, v4
	v_mov_b32_e32 v83, v4
	v_mov_b32_e32 v92, v4
	v_mov_b32_e32 v93, v4
	v_mov_b32_e32 v94, v4
	v_mov_b32_e32 v95, v4
	v_mov_b32_e32 v96, v4
	v_mov_b32_e32 v97, v4
	v_mov_b32_e32 v98, v4
	v_mov_b32_e32 v99, v4
	v_mov_b32_e32 v108, v4
	v_mov_b32_e32 v109, v4
	v_mov_b32_e32 v110, v4
	v_mov_b32_e32 v111, v4
	v_mov_b32_e32 v112, v4
	v_mov_b32_e32 v113, v4
	v_mov_b32_e32 v114, v4
	v_mov_b32_e32 v115, v4
	v_mov_b32_e32 v124, v4
	v_mov_b32_e32 v125, v4
	v_mov_b32_e32 v126, v4
	v_mov_b32_e32 v127, v4
	v_mov_b32_e32 v128, v4
	v_mov_b32_e32 v129, v4
	v_mov_b32_e32 v130, v4
	v_mov_b32_e32 v131, v4
	.p2align	6
